# EpiIn: hoist the 8 per-row rstd loads in front of the K-loop, drop the 8 serialising vmcnt(0) per tile
# baseline (speedup 1.0000x reference)
.LBB0_366:
	s_ashr_i32 s91, s90, 31
	s_lshl_b64 s[26:27], s[90:91], 19
	s_add_u32 s92, s36, s26
	s_addc_u32 s93, s37, s27
	s_and_b64 s[26:27], s[42:43], exec
	s_cselect_b32 s26, s93, s45
	s_cselect_b32 s27, s92, s44
	s_ashr_i32 s89, s88, 31
	s_lshl_b64 s[48:49], s[88:89], 19
	s_add_u32 s94, s38, s48
	s_addc_u32 s95, s39, s49
	s_and_b64 s[48:49], s[42:43], exec
	s_cselect_b32 s69, s95, s47
	s_cselect_b32 s70, s94, s46
	s_add_u32 s71, s46, 0x100
	v_mov_b32_e32 v2, 0
	s_addc_u32 s72, s47, 0
	s_mov_b32 s73, -2
	v_mov_b32_e32 v3, v2
	v_mov_b32_e32 v4, v2
	v_mov_b32_e32 v5, v2
	v_mov_b32_e32 v6, v2
	v_mov_b32_e32 v7, v2
	v_mov_b32_e32 v8, v2
	v_mov_b32_e32 v9, v2
	v_mov_b32_e32 v18, v2
	v_mov_b32_e32 v19, v2
	v_mov_b32_e32 v20, v2
	v_mov_b32_e32 v21, v2
	v_mov_b32_e32 v22, v2
	v_mov_b32_e32 v23, v2
	v_mov_b32_e32 v24, v2
	v_mov_b32_e32 v25, v2
	s_waitcnt vmcnt(23)
	v_mov_b32_e32 v34, v2
	v_mov_b32_e32 v35, v2
	v_mov_b32_e32 v36, v2
	v_mov_b32_e32 v37, v2
	s_waitcnt vmcnt(22)
	v_mov_b32_e32 v38, v2
	v_mov_b32_e32 v39, v2
	v_mov_b32_e32 v40, v2
	v_mov_b32_e32 v41, v2
	s_waitcnt vmcnt(19)
	v_mov_b32_e32 v50, v2
	v_mov_b32_e32 v51, v2
	v_mov_b32_e32 v52, v2
	v_mov_b32_e32 v53, v2
	s_waitcnt vmcnt(18)
	v_mov_b32_e32 v54, v2
	v_mov_b32_e32 v55, v2
	v_mov_b32_e32 v56, v2
	v_mov_b32_e32 v57, v2
	v_mov_b32_e32 v10, v2
	v_mov_b32_e32 v11, v2
	v_mov_b32_e32 v12, v2
	v_mov_b32_e32 v13, v2
	v_mov_b32_e32 v14, v2
	v_mov_b32_e32 v15, v2
	v_mov_b32_e32 v16, v2
	v_mov_b32_e32 v17, v2
	v_mov_b32_e32 v26, v2
	v_mov_b32_e32 v27, v2
	v_mov_b32_e32 v28, v2
	v_mov_b32_e32 v29, v2
	v_mov_b32_e32 v30, v2
	v_mov_b32_e32 v31, v2
	v_mov_b32_e32 v32, v2
	v_mov_b32_e32 v33, v2
	v_mov_b32_e32 v42, v2
	v_mov_b32_e32 v43, v2
	v_mov_b32_e32 v44, v2
	v_mov_b32_e32 v45, v2
	v_mov_b32_e32 v46, v2
	v_mov_b32_e32 v47, v2
	v_mov_b32_e32 v48, v2
	v_mov_b32_e32 v49, v2
	s_waitcnt vmcnt(17)
	v_mov_b32_e32 v58, v2
	v_mov_b32_e32 v59, v2
	v_mov_b32_e32 v60, v2
	v_mov_b32_e32 v61, v2
	s_waitcnt vmcnt(16)
	v_mov_b32_e32 v62, v2
	v_mov_b32_e32 v63, v2
	v_mov_b32_e32 v64, v2
	v_mov_b32_e32 v65, v2
	s_waitcnt vmcnt(15)
	v_mov_b32_e32 v66, v2
	v_mov_b32_e32 v67, v2
	v_mov_b32_e32 v68, v2
	v_mov_b32_e32 v69, v2
	s_waitcnt vmcnt(14)
	v_mov_b32_e32 v70, v2
	v_mov_b32_e32 v71, v2
	v_mov_b32_e32 v72, v2
	v_mov_b32_e32 v73, v2
	s_waitcnt vmcnt(11)
	v_mov_b32_e32 v82, v2
	v_mov_b32_e32 v83, v2
	v_mov_b32_e32 v84, v2
	v_mov_b32_e32 v85, v2
	s_waitcnt vmcnt(10)
	v_mov_b32_e32 v86, v2
	v_mov_b32_e32 v87, v2
	v_mov_b32_e32 v88, v2
	v_mov_b32_e32 v89, v2
	s_waitcnt vmcnt(7)
	v_mov_b32_e32 v98, v2
	v_mov_b32_e32 v99, v2
	v_mov_b32_e32 v100, v2
	v_mov_b32_e32 v101, v2
	s_waitcnt vmcnt(6)
	v_mov_b32_e32 v102, v2
	v_mov_b32_e32 v103, v2
	v_mov_b32_e32 v104, v2
	v_mov_b32_e32 v105, v2
	v_mov_b32_e32 v114, v2
	v_mov_b32_e32 v115, v2
	v_mov_b32_e32 v116, v2
	v_mov_b32_e32 v117, v2
	v_mov_b32_e32 v118, v2
	v_mov_b32_e32 v119, v2
	v_mov_b32_e32 v120, v2
	v_mov_b32_e32 v121, v2
	v_mov_b32_e32 v74, v2
	v_mov_b32_e32 v75, v2
	v_mov_b32_e32 v76, v2
	v_mov_b32_e32 v77, v2
	v_mov_b32_e32 v78, v2
	v_mov_b32_e32 v79, v2
	v_mov_b32_e32 v80, v2
	v_mov_b32_e32 v81, v2
	v_mov_b32_e32 v90, v2
	v_mov_b32_e32 v91, v2
	v_mov_b32_e32 v92, v2
	v_mov_b32_e32 v93, v2
	v_mov_b32_e32 v94, v2
	v_mov_b32_e32 v95, v2
	v_mov_b32_e32 v96, v2
	v_mov_b32_e32 v97, v2
	s_waitcnt vmcnt(5)
	v_mov_b32_e32 v106, v2
	v_mov_b32_e32 v107, v2
	v_mov_b32_e32 v108, v2
	v_mov_b32_e32 v109, v2
	s_waitcnt vmcnt(4)
	v_mov_b32_e32 v110, v2
	v_mov_b32_e32 v111, v2
	v_mov_b32_e32 v112, v2
	v_mov_b32_e32 v113, v2
	v_mov_b32_e32 v122, v2
	v_mov_b32_e32 v123, v2
	v_mov_b32_e32 v124, v2
	v_mov_b32_e32 v125, v2
	v_mov_b32_e32 v126, v2
	v_mov_b32_e32 v127, v2
	v_mov_b32_e32 v128, v2
	v_mov_b32_e32 v129, v2
	v_lshl_add_u32 v240, s68, 8, v148
	v_ashrrev_i32_e32 v241, 31, v240
	v_lshl_add_u64 v[240:241], v[240:241], 2, s[86:87]
	global_load_dword v232, v[240:241], off
	global_load_dword v233, v[240:241], off offset:64
	global_load_dword v234, v[240:241], off offset:128
	global_load_dword v235, v[240:241], off offset:192
	global_load_dword v236, v[240:241], off offset:512
	global_load_dword v237, v[240:241], off offset:576
	global_load_dword v238, v[240:241], off offset:640
	global_load_dword v239, v[240:241], off offset:704

.LBB0_375:
	v_ashrrev_i32_e32 v135, 31, v134
	v_lshl_add_u64 v[138:139], v[134:135], 2, s[86:87]
	v_mov_b32_e32 v0, v232
	v_mov_b32_e32 v130, v126
	v_mov_b32_e32 v131, v118
	v_lshl_or_b32 v136, s19, 7, v149
	v_readlane_b32 s26, v252, 17
	v_ashrrev_i32_e32 v137, 31, v136
	v_readlane_b32 s27, v252, 18
	v_pk_mul_f32 v[130:131], v[130:131], v[0:1] op_sel_hi:[1,0]
	s_nop 0
	v_mul_f32_e32 v130, v130, v131
	v_mul_f32_e32 v131, 0xbfb8aa3b, v131
	v_exp_f32_e32 v131, v131
	s_nop 0
	v_add_f32_e32 v131, 1.0, v131
	v_rcp_f32_e32 v131, v131
	s_nop 0
	v_mul_f32_e32 v132, v130, v131
	v_mov_b32_e32 v130, v122
	v_mov_b32_e32 v131, v114
	v_pk_mul_f32 v[130:131], v[130:131], v[0:1] op_sel_hi:[1,0]
	s_nop 0
	v_mul_f32_e32 v130, v130, v131
	v_mul_f32_e32 v131, 0xbfb8aa3b, v131
	v_exp_f32_e32 v131, v131
	s_nop 0
	v_add_f32_e32 v131, 1.0, v131
	v_rcp_f32_e32 v131, v131
	s_nop 0
	v_mul_f32_e32 v133, v130, v131
	v_mov_b32_e32 v130, v127
	v_mov_b32_e32 v131, v119
	v_pk_mul_f32 v[130:131], v[130:131], v[0:1] op_sel_hi:[1,0]
	s_nop 0
	v_mul_f32_e32 v130, v130, v131
	v_mul_f32_e32 v131, 0xbfb8aa3b, v131
	v_exp_f32_e32 v131, v131
	s_nop 0
	v_add_f32_e32 v131, 1.0, v131
	v_rcp_f32_e32 v131, v131
	s_nop 0
	v_mul_f32_e32 v140, v130, v131
	v_mov_b32_e32 v130, v123
	v_mov_b32_e32 v131, v115
	v_pk_mul_f32 v[130:131], v[130:131], v[0:1] op_sel_hi:[1,0]
	s_nop 0
	v_mul_f32_e32 v130, v130, v131
	v_mul_f32_e32 v131, 0xbfb8aa3b, v131
	v_exp_f32_e32 v131, v131
	s_nop 0
	v_add_f32_e32 v131, 1.0, v131
	v_rcp_f32_e32 v131, v131
	s_nop 0
	v_mul_f32_e32 v141, v130, v131
	v_mov_b32_e32 v130, v128
	v_mov_b32_e32 v131, v120
	v_pk_mul_f32 v[130:131], v[130:131], v[0:1] op_sel_hi:[1,0]
	s_nop 0
	v_mul_f32_e32 v130, v130, v131
	v_mul_f32_e32 v131, 0xbfb8aa3b, v131
	v_exp_f32_e32 v131, v131
	s_nop 0
	v_add_f32_e32 v131, 1.0, v131
	v_rcp_f32_e32 v131, v131
	s_nop 0
	v_mul_f32_e32 v142, v130, v131
	v_mov_b32_e32 v130, v124
	v_mov_b32_e32 v131, v116
	v_pk_mul_f32 v[130:131], v[130:131], v[0:1] op_sel_hi:[1,0]
	s_nop 0
	v_mul_f32_e32 v130, v130, v131
	v_mul_f32_e32 v131, 0xbfb8aa3b, v131
	v_exp_f32_e32 v131, v131
	s_nop 0
	v_add_f32_e32 v131, 1.0, v131
	v_rcp_f32_e32 v131, v131
	s_nop 0
	v_mul_f32_e32 v143, v130, v131
	v_mov_b32_e32 v130, v129
	v_mov_b32_e32 v131, v121
	v_pk_mul_f32 v[130:131], v[130:131], v[0:1] op_sel_hi:[1,0]
	s_nop 0
	v_mul_f32_e32 v130, v130, v131
	v_mul_f32_e32 v131, 0xbfb8aa3b, v131
	v_exp_f32_e32 v131, v131
	s_nop 0
	v_add_f32_e32 v131, 1.0, v131
	v_rcp_f32_e32 v131, v131
	s_nop 0
	v_mul_f32_e32 v152, v130, v131
	v_mov_b32_e32 v130, v125
	v_mov_b32_e32 v131, v117
	v_pk_mul_f32 v[130:131], v[130:131], v[0:1] op_sel_hi:[1,0]
	s_nop 0
	v_mul_f32_e32 v0, v130, v131
	v_mul_f32_e32 v130, 0xbfb8aa3b, v131
	v_exp_f32_e32 v130, v130
	s_nop 0
	v_add_f32_e32 v130, 1.0, v130
	v_rcp_f32_e32 v130, v130
	s_nop 0
	v_mul_f32_e32 v0, v0, v130
	v_cvt_pk_bf16_f32 v130, v132, v140
	v_cvt_pk_bf16_f32 v131, v142, v152
	v_cvt_pk_bf16_f32 v132, v133, v141
	v_lshlrev_b64 v[140:141], 12, v[134:135]
	v_cvt_pk_bf16_f32 v133, v143, v0
	v_lshl_add_u64 v[142:143], s[26:27], 0, v[140:141]
	v_lshlrev_b64 v[140:141], 1, v[136:137]
	v_lshl_add_u64 v[136:137], v[142:143], 0, v[140:141]
	global_store_dwordx4 v[136:137], v[130:133], off
	v_mov_b32_e32 v0, v233
	v_or_b32_e32 v142, 16, v134
	v_mov_b32_e32 v130, v110
	v_mov_b32_e32 v131, v102
	v_ashrrev_i32_e32 v143, 31, v142
	v_lshlrev_b64 v[142:143], 12, v[142:143]
	v_lshl_add_u64 v[142:143], s[26:27], 0, v[142:143]
	v_lshl_add_u64 v[142:143], v[142:143], 0, v[140:141]
	v_pk_mul_f32 v[130:131], v[130:131], v[0:1] op_sel_hi:[1,0]
	s_nop 0
	v_mul_f32_e32 v130, v130, v131
	v_mul_f32_e32 v131, 0xbfb8aa3b, v131
	v_exp_f32_e32 v131, v131
	s_nop 0
	v_add_f32_e32 v131, 1.0, v131
	v_rcp_f32_e32 v131, v131
	s_nop 0
	v_mul_f32_e32 v132, v130, v131
	v_mov_b32_e32 v130, v106
	v_mov_b32_e32 v131, v98
	v_pk_mul_f32 v[130:131], v[130:131], v[0:1] op_sel_hi:[1,0]
	s_nop 0
	v_mul_f32_e32 v130, v130, v131
	v_mul_f32_e32 v131, 0xbfb8aa3b, v131
	v_exp_f32_e32 v131, v131
	s_nop 0
	v_add_f32_e32 v131, 1.0, v131
	v_rcp_f32_e32 v131, v131
	s_nop 0
	v_mul_f32_e32 v133, v130, v131
	v_mov_b32_e32 v130, v111
	v_mov_b32_e32 v131, v103
	v_pk_mul_f32 v[130:131], v[130:131], v[0:1] op_sel_hi:[1,0]
	s_nop 0
	v_mul_f32_e32 v130, v130, v131
	v_mul_f32_e32 v131, 0xbfb8aa3b, v131
	v_exp_f32_e32 v131, v131
	s_nop 0
	v_add_f32_e32 v131, 1.0, v131
	v_rcp_f32_e32 v131, v131
	s_nop 0
	v_mul_f32_e32 v135, v130, v131
	v_mov_b32_e32 v130, v107
	v_mov_b32_e32 v131, v99
	v_pk_mul_f32 v[130:131], v[130:131], v[0:1] op_sel_hi:[1,0]
	s_nop 0
	v_mul_f32_e32 v130, v130, v131
	v_mul_f32_e32 v131, 0xbfb8aa3b, v131
	v_exp_f32_e32 v131, v131
	s_nop 0
	v_add_f32_e32 v131, 1.0, v131
	v_rcp_f32_e32 v131, v131
	s_nop 0
	v_mul_f32_e32 v152, v130, v131
	v_mov_b32_e32 v130, v112
	v_mov_b32_e32 v131, v104
	v_pk_mul_f32 v[130:131], v[130:131], v[0:1] op_sel_hi:[1,0]
	s_nop 0
	v_mul_f32_e32 v130, v130, v131
	v_mul_f32_e32 v131, 0xbfb8aa3b, v131
	v_exp_f32_e32 v131, v131
	s_nop 0
	v_add_f32_e32 v131, 1.0, v131
	v_rcp_f32_e32 v131, v131
	s_nop 0
	v_mul_f32_e32 v153, v130, v131
	v_mov_b32_e32 v130, v108
	v_mov_b32_e32 v131, v100
	v_pk_mul_f32 v[130:131], v[130:131], v[0:1] op_sel_hi:[1,0]
	s_nop 0
	v_mul_f32_e32 v130, v130, v131
	v_mul_f32_e32 v131, 0xbfb8aa3b, v131
	v_exp_f32_e32 v131, v131
	s_nop 0
	v_add_f32_e32 v131, 1.0, v131
	v_rcp_f32_e32 v131, v131
	s_nop 0
	v_mul_f32_e32 v154, v130, v131
	v_mov_b32_e32 v130, v113
	v_mov_b32_e32 v131, v105
	v_pk_mul_f32 v[130:131], v[130:131], v[0:1] op_sel_hi:[1,0]
	s_nop 0
	v_mul_f32_e32 v130, v130, v131
	v_mul_f32_e32 v131, 0xbfb8aa3b, v131
	v_exp_f32_e32 v131, v131
	s_nop 0
	v_add_f32_e32 v131, 1.0, v131
	v_rcp_f32_e32 v131, v131
	s_nop 0
	v_mul_f32_e32 v155, v130, v131
	v_mov_b32_e32 v130, v109
	v_mov_b32_e32 v131, v101
	v_pk_mul_f32 v[130:131], v[130:131], v[0:1] op_sel_hi:[1,0]
	s_nop 0
	v_mul_f32_e32 v0, v130, v131
	v_mul_f32_e32 v130, 0xbfb8aa3b, v131
	v_exp_f32_e32 v130, v130
	s_nop 0
	v_add_f32_e32 v130, 1.0, v130
	v_rcp_f32_e32 v130, v130
	s_nop 0
	v_mul_f32_e32 v0, v0, v130
	v_cvt_pk_bf16_f32 v130, v132, v135
	v_cvt_pk_bf16_f32 v131, v153, v155
	v_cvt_pk_bf16_f32 v132, v133, v152
	v_cvt_pk_bf16_f32 v133, v154, v0
	global_store_dwordx4 v[142:143], v[130:133], off
	v_mov_b32_e32 v0, v234
	v_or_b32_e32 v142, 32, v134
	v_mov_b32_e32 v130, v94
	v_mov_b32_e32 v131, v86
	v_ashrrev_i32_e32 v143, 31, v142
	v_lshlrev_b64 v[142:143], 12, v[142:143]
	v_lshl_add_u64 v[142:143], s[26:27], 0, v[142:143]
	v_lshl_add_u64 v[142:143], v[142:143], 0, v[140:141]
	v_pk_mul_f32 v[130:131], v[130:131], v[0:1] op_sel_hi:[1,0]
	s_nop 0
	v_mul_f32_e32 v130, v130, v131
	v_mul_f32_e32 v131, 0xbfb8aa3b, v131
	v_exp_f32_e32 v131, v131
	s_nop 0
	v_add_f32_e32 v131, 1.0, v131
	v_rcp_f32_e32 v131, v131
	s_nop 0
	v_mul_f32_e32 v132, v130, v131
	v_mov_b32_e32 v130, v90
	v_mov_b32_e32 v131, v82
	v_pk_mul_f32 v[130:131], v[130:131], v[0:1] op_sel_hi:[1,0]
	s_nop 0
	v_mul_f32_e32 v130, v130, v131
	v_mul_f32_e32 v131, 0xbfb8aa3b, v131
	v_exp_f32_e32 v131, v131
	s_nop 0
	v_add_f32_e32 v131, 1.0, v131
	v_rcp_f32_e32 v131, v131
	s_nop 0
	v_mul_f32_e32 v133, v130, v131
	v_mov_b32_e32 v130, v95
	v_mov_b32_e32 v131, v87
	v_pk_mul_f32 v[130:131], v[130:131], v[0:1] op_sel_hi:[1,0]
	s_nop 0
	v_mul_f32_e32 v130, v130, v131
	v_mul_f32_e32 v131, 0xbfb8aa3b, v131
	v_exp_f32_e32 v131, v131
	s_nop 0
	v_add_f32_e32 v131, 1.0, v131
	v_rcp_f32_e32 v131, v131
	s_nop 0
	v_mul_f32_e32 v135, v130, v131
	v_mov_b32_e32 v130, v91
	v_mov_b32_e32 v131, v83
	v_pk_mul_f32 v[130:131], v[130:131], v[0:1] op_sel_hi:[1,0]
	s_nop 0
	v_mul_f32_e32 v130, v130, v131
	v_mul_f32_e32 v131, 0xbfb8aa3b, v131
	v_exp_f32_e32 v131, v131
	s_nop 0
	v_add_f32_e32 v131, 1.0, v131
	v_rcp_f32_e32 v131, v131
	s_nop 0
	v_mul_f32_e32 v152, v130, v131
	v_mov_b32_e32 v130, v96
	v_mov_b32_e32 v131, v88
	v_pk_mul_f32 v[130:131], v[130:131], v[0:1] op_sel_hi:[1,0]
	s_nop 0
	v_mul_f32_e32 v130, v130, v131
	v_mul_f32_e32 v131, 0xbfb8aa3b, v131
	v_exp_f32_e32 v131, v131
	s_nop 0
	v_add_f32_e32 v131, 1.0, v131
	v_rcp_f32_e32 v131, v131
	s_nop 0
	v_mul_f32_e32 v153, v130, v131
	v_mov_b32_e32 v130, v92
	v_mov_b32_e32 v131, v84
	v_pk_mul_f32 v[130:131], v[130:131], v[0:1] op_sel_hi:[1,0]
	s_nop 0
	v_mul_f32_e32 v130, v130, v131
	v_mul_f32_e32 v131, 0xbfb8aa3b, v131
	v_exp_f32_e32 v131, v131
	s_nop 0
	v_add_f32_e32 v131, 1.0, v131
	v_rcp_f32_e32 v131, v131
	s_nop 0
	v_mul_f32_e32 v154, v130, v131
	v_mov_b32_e32 v130, v97
	v_mov_b32_e32 v131, v89
	v_pk_mul_f32 v[130:131], v[130:131], v[0:1] op_sel_hi:[1,0]
	s_nop 0
	v_mul_f32_e32 v130, v130, v131
	v_mul_f32_e32 v131, 0xbfb8aa3b, v131
	v_exp_f32_e32 v131, v131
	s_nop 0
	v_add_f32_e32 v131, 1.0, v131
	v_rcp_f32_e32 v131, v131
	s_nop 0
	v_mul_f32_e32 v155, v130, v131
	v_mov_b32_e32 v130, v93
	v_mov_b32_e32 v131, v85
	v_pk_mul_f32 v[130:131], v[130:131], v[0:1] op_sel_hi:[1,0]
	s_nop 0
	v_mul_f32_e32 v0, v130, v131
	v_mul_f32_e32 v130, 0xbfb8aa3b, v131
	v_exp_f32_e32 v130, v130
	s_nop 0
	v_add_f32_e32 v130, 1.0, v130
	v_rcp_f32_e32 v130, v130
	s_nop 0
	v_mul_f32_e32 v0, v0, v130
	v_cvt_pk_bf16_f32 v130, v132, v135
	v_cvt_pk_bf16_f32 v131, v153, v155
	v_cvt_pk_bf16_f32 v132, v133, v152
	v_cvt_pk_bf16_f32 v133, v154, v0
	global_store_dwordx4 v[142:143], v[130:133], off
	v_mov_b32_e32 v0, v235
	v_or_b32_e32 v142, 48, v134
	v_mov_b32_e32 v130, v78
	v_mov_b32_e32 v131, v70
	v_ashrrev_i32_e32 v143, 31, v142
	v_lshlrev_b64 v[142:143], 12, v[142:143]
	v_lshl_add_u64 v[142:143], s[26:27], 0, v[142:143]
	v_lshl_add_u64 v[140:141], v[142:143], 0, v[140:141]
	s_mov_b32 s26, 0x80000
	v_pk_mul_f32 v[130:131], v[130:131], v[0:1] op_sel_hi:[1,0]
	s_nop 0
	v_mul_f32_e32 v130, v130, v131
	v_mul_f32_e32 v131, 0xbfb8aa3b, v131
	v_exp_f32_e32 v131, v131
	s_nop 0
	v_add_f32_e32 v131, 1.0, v131
	v_rcp_f32_e32 v131, v131
	s_nop 0
	v_mul_f32_e32 v132, v130, v131
	v_mov_b32_e32 v130, v74
	v_mov_b32_e32 v131, v66
	v_pk_mul_f32 v[130:131], v[130:131], v[0:1] op_sel_hi:[1,0]
	s_nop 0
	v_mul_f32_e32 v130, v130, v131
	v_mul_f32_e32 v131, 0xbfb8aa3b, v131
	v_exp_f32_e32 v131, v131
	s_nop 0
	v_add_f32_e32 v131, 1.0, v131
	v_rcp_f32_e32 v131, v131
	s_nop 0
	v_mul_f32_e32 v133, v130, v131
	v_mov_b32_e32 v130, v79
	v_mov_b32_e32 v131, v71
	v_pk_mul_f32 v[130:131], v[130:131], v[0:1] op_sel_hi:[1,0]
	s_nop 0
	v_mul_f32_e32 v130, v130, v131
	v_mul_f32_e32 v131, 0xbfb8aa3b, v131
	v_exp_f32_e32 v131, v131
	s_nop 0
	v_add_f32_e32 v131, 1.0, v131
	v_rcp_f32_e32 v131, v131
	s_nop 0
	v_mul_f32_e32 v135, v130, v131
	v_mov_b32_e32 v130, v75
	v_mov_b32_e32 v131, v67
	v_pk_mul_f32 v[130:131], v[130:131], v[0:1] op_sel_hi:[1,0]
	s_nop 0
	v_mul_f32_e32 v130, v130, v131
	v_mul_f32_e32 v131, 0xbfb8aa3b, v131
	v_exp_f32_e32 v131, v131
	s_nop 0
	v_add_f32_e32 v131, 1.0, v131
	v_rcp_f32_e32 v131, v131
	s_nop 0
	v_mul_f32_e32 v152, v130, v131
	v_mov_b32_e32 v130, v80
	v_mov_b32_e32 v131, v72
	v_pk_mul_f32 v[130:131], v[130:131], v[0:1] op_sel_hi:[1,0]
	s_nop 0
	v_mul_f32_e32 v130, v130, v131
	v_mul_f32_e32 v131, 0xbfb8aa3b, v131
	v_exp_f32_e32 v131, v131
	s_nop 0
	v_add_f32_e32 v131, 1.0, v131
	v_rcp_f32_e32 v131, v131
	s_nop 0
	v_mul_f32_e32 v153, v130, v131
	v_mov_b32_e32 v130, v76
	v_mov_b32_e32 v131, v68
	v_pk_mul_f32 v[130:131], v[130:131], v[0:1] op_sel_hi:[1,0]
	s_nop 0
	v_mul_f32_e32 v130, v130, v131
	v_mul_f32_e32 v131, 0xbfb8aa3b, v131
	v_exp_f32_e32 v131, v131
	s_nop 0
	v_add_f32_e32 v131, 1.0, v131
	v_rcp_f32_e32 v131, v131
	s_nop 0
	v_mul_f32_e32 v154, v130, v131
	v_mov_b32_e32 v130, v81
	v_mov_b32_e32 v131, v73
	v_pk_mul_f32 v[130:131], v[130:131], v[0:1] op_sel_hi:[1,0]
	s_nop 0
	v_mul_f32_e32 v130, v130, v131
	v_mul_f32_e32 v131, 0xbfb8aa3b, v131
	v_exp_f32_e32 v131, v131
	s_nop 0
	v_add_f32_e32 v131, 1.0, v131
	v_rcp_f32_e32 v131, v131
	s_nop 0
	v_mul_f32_e32 v155, v130, v131
	v_mov_b32_e32 v130, v77
	v_mov_b32_e32 v131, v69
	v_pk_mul_f32 v[130:131], v[130:131], v[0:1] op_sel_hi:[1,0]
	s_nop 0
	v_mul_f32_e32 v0, v130, v131
	v_mul_f32_e32 v130, 0xbfb8aa3b, v131
	v_exp_f32_e32 v130, v130
	s_nop 0
	v_add_f32_e32 v130, 1.0, v130
	v_rcp_f32_e32 v130, v130
	s_nop 0
	v_mul_f32_e32 v0, v0, v130
	v_cvt_pk_bf16_f32 v130, v132, v135
	v_cvt_pk_bf16_f32 v131, v153, v155
	v_cvt_pk_bf16_f32 v132, v133, v152
	v_cvt_pk_bf16_f32 v133, v154, v0
	global_store_dwordx4 v[140:141], v[130:133], off
	v_mov_b32_e32 v0, v236
	s_nop 0
	v_mov_b32_e32 v130, v62
	v_mov_b32_e32 v131, v54
	v_pk_mul_f32 v[130:131], v[130:131], v[0:1] op_sel_hi:[1,0]
	s_nop 0
	v_mul_f32_e32 v130, v130, v131
	v_mul_f32_e32 v131, 0xbfb8aa3b, v131
	v_exp_f32_e32 v131, v131
	s_nop 0
	v_add_f32_e32 v131, 1.0, v131
	v_rcp_f32_e32 v131, v131
	s_nop 0
	v_mul_f32_e32 v132, v130, v131
	v_mov_b32_e32 v130, v58
	v_mov_b32_e32 v131, v50
	v_pk_mul_f32 v[130:131], v[130:131], v[0:1] op_sel_hi:[1,0]
	s_nop 0
	v_mul_f32_e32 v130, v130, v131
	v_mul_f32_e32 v131, 0xbfb8aa3b, v131
	v_exp_f32_e32 v131, v131
	s_nop 0
	v_add_f32_e32 v131, 1.0, v131
	v_rcp_f32_e32 v131, v131
	s_nop 0
	v_mul_f32_e32 v133, v130, v131
	v_mov_b32_e32 v130, v63
	v_mov_b32_e32 v131, v55
	v_pk_mul_f32 v[130:131], v[130:131], v[0:1] op_sel_hi:[1,0]
	s_nop 0
	v_mul_f32_e32 v130, v130, v131
	v_mul_f32_e32 v131, 0xbfb8aa3b, v131
	v_exp_f32_e32 v131, v131
	s_nop 0
	v_add_f32_e32 v131, 1.0, v131
	v_rcp_f32_e32 v131, v131
	s_nop 0
	v_mul_f32_e32 v135, v130, v131
	v_mov_b32_e32 v130, v59
	v_mov_b32_e32 v131, v51
	v_pk_mul_f32 v[130:131], v[130:131], v[0:1] op_sel_hi:[1,0]
	s_nop 0
	v_mul_f32_e32 v130, v130, v131
	v_mul_f32_e32 v131, 0xbfb8aa3b, v131
	v_exp_f32_e32 v131, v131
	s_nop 0
	v_add_f32_e32 v131, 1.0, v131
	v_rcp_f32_e32 v131, v131
	s_nop 0
	v_mul_f32_e32 v140, v130, v131
	v_mov_b32_e32 v130, v64
	v_mov_b32_e32 v131, v56
	v_pk_mul_f32 v[130:131], v[130:131], v[0:1] op_sel_hi:[1,0]
	s_nop 0
	v_mul_f32_e32 v130, v130, v131
	v_mul_f32_e32 v131, 0xbfb8aa3b, v131
	v_exp_f32_e32 v131, v131
	s_nop 0
	v_add_f32_e32 v131, 1.0, v131
	v_rcp_f32_e32 v131, v131
	s_nop 0
	v_mul_f32_e32 v141, v130, v131
	v_mov_b32_e32 v130, v60
	v_mov_b32_e32 v131, v52
	v_pk_mul_f32 v[130:131], v[130:131], v[0:1] op_sel_hi:[1,0]
	s_nop 0
	v_mul_f32_e32 v130, v130, v131
	v_mul_f32_e32 v131, 0xbfb8aa3b, v131
	v_exp_f32_e32 v131, v131
	s_nop 0
	v_add_f32_e32 v131, 1.0, v131
	v_rcp_f32_e32 v131, v131
	s_nop 0
	v_mul_f32_e32 v142, v130, v131
	v_mov_b32_e32 v130, v65
	v_mov_b32_e32 v131, v57
	v_pk_mul_f32 v[130:131], v[130:131], v[0:1] op_sel_hi:[1,0]
	s_nop 0
	v_mul_f32_e32 v130, v130, v131
	v_mul_f32_e32 v131, 0xbfb8aa3b, v131
	v_exp_f32_e32 v131, v131
	s_nop 0
	v_add_f32_e32 v131, 1.0, v131
	v_rcp_f32_e32 v131, v131
	s_nop 0
	v_mul_f32_e32 v143, v130, v131
	v_mov_b32_e32 v130, v61
	v_mov_b32_e32 v131, v53
	v_pk_mul_f32 v[130:131], v[130:131], v[0:1] op_sel_hi:[1,0]
	s_nop 0
	v_mul_f32_e32 v0, v130, v131
	v_mul_f32_e32 v130, 0xbfb8aa3b, v131
	v_exp_f32_e32 v130, v130
	s_nop 0
	v_add_f32_e32 v130, 1.0, v130
	v_rcp_f32_e32 v130, v130
	s_nop 0
	v_mul_f32_e32 v0, v0, v130
	v_cvt_pk_bf16_f32 v130, v132, v135
	v_cvt_pk_bf16_f32 v131, v141, v143
	v_cvt_pk_bf16_f32 v132, v133, v140
	v_add_co_u32_e32 v140, vcc, s26, v136
	v_cvt_pk_bf16_f32 v133, v142, v0
	s_mov_b32 s26, 0x90000
	s_nop 0
	v_addc_co_u32_e32 v141, vcc, 0, v137, vcc
	global_store_dwordx4 v[140:141], v[130:133], off
	v_mov_b32_e32 v0, v237
	s_nop 0
	v_mov_b32_e32 v130, v46
	v_mov_b32_e32 v131, v38
	v_pk_mul_f32 v[130:131], v[130:131], v[0:1] op_sel_hi:[1,0]
	s_nop 0
	v_mul_f32_e32 v130, v130, v131
	v_mul_f32_e32 v131, 0xbfb8aa3b, v131
	v_exp_f32_e32 v131, v131
	s_nop 0
	v_add_f32_e32 v131, 1.0, v131
	v_rcp_f32_e32 v131, v131
	s_nop 0
	v_mul_f32_e32 v132, v130, v131
	v_mov_b32_e32 v130, v42
	v_mov_b32_e32 v131, v34
	v_pk_mul_f32 v[130:131], v[130:131], v[0:1] op_sel_hi:[1,0]
	s_nop 0
	v_mul_f32_e32 v130, v130, v131
	v_mul_f32_e32 v131, 0xbfb8aa3b, v131
	v_exp_f32_e32 v131, v131
	s_nop 0
	v_add_f32_e32 v131, 1.0, v131
	v_rcp_f32_e32 v131, v131
	s_nop 0
	v_mul_f32_e32 v133, v130, v131
	v_mov_b32_e32 v130, v47
	v_mov_b32_e32 v131, v39
	v_pk_mul_f32 v[130:131], v[130:131], v[0:1] op_sel_hi:[1,0]
	s_nop 0
	v_mul_f32_e32 v130, v130, v131
	v_mul_f32_e32 v131, 0xbfb8aa3b, v131
	v_exp_f32_e32 v131, v131
	s_nop 0
	v_add_f32_e32 v131, 1.0, v131
	v_rcp_f32_e32 v131, v131
	s_nop 0
	v_mul_f32_e32 v135, v130, v131
	v_mov_b32_e32 v130, v43
	v_mov_b32_e32 v131, v35
	v_pk_mul_f32 v[130:131], v[130:131], v[0:1] op_sel_hi:[1,0]
	s_nop 0
	v_mul_f32_e32 v130, v130, v131
	v_mul_f32_e32 v131, 0xbfb8aa3b, v131
	v_exp_f32_e32 v131, v131
	s_nop 0
	v_add_f32_e32 v131, 1.0, v131
	v_rcp_f32_e32 v131, v131
	s_nop 0
	v_mul_f32_e32 v140, v130, v131
	v_mov_b32_e32 v130, v48
	v_mov_b32_e32 v131, v40
	v_pk_mul_f32 v[130:131], v[130:131], v[0:1] op_sel_hi:[1,0]
	s_nop 0
	v_mul_f32_e32 v130, v130, v131
	v_mul_f32_e32 v131, 0xbfb8aa3b, v131
	v_exp_f32_e32 v131, v131
	s_nop 0
	v_add_f32_e32 v131, 1.0, v131
	v_rcp_f32_e32 v131, v131
	s_nop 0
	v_mul_f32_e32 v141, v130, v131
	v_mov_b32_e32 v130, v44
	v_mov_b32_e32 v131, v36
	v_pk_mul_f32 v[130:131], v[130:131], v[0:1] op_sel_hi:[1,0]
	s_nop 0
	v_mul_f32_e32 v130, v130, v131
	v_mul_f32_e32 v131, 0xbfb8aa3b, v131
	v_exp_f32_e32 v131, v131
	s_nop 0
	v_add_f32_e32 v131, 1.0, v131
	v_rcp_f32_e32 v131, v131
	s_nop 0
	v_mul_f32_e32 v142, v130, v131
	v_mov_b32_e32 v130, v49
	v_mov_b32_e32 v131, v41
	v_pk_mul_f32 v[130:131], v[130:131], v[0:1] op_sel_hi:[1,0]
	s_nop 0
	v_mul_f32_e32 v130, v130, v131
	v_mul_f32_e32 v131, 0xbfb8aa3b, v131
	v_exp_f32_e32 v131, v131
	s_nop 0
	v_add_f32_e32 v131, 1.0, v131
	v_rcp_f32_e32 v131, v131
	s_nop 0
	v_mul_f32_e32 v143, v130, v131
	v_mov_b32_e32 v130, v45
	v_mov_b32_e32 v131, v37
	v_pk_mul_f32 v[130:131], v[130:131], v[0:1] op_sel_hi:[1,0]
	s_nop 0
	v_mul_f32_e32 v0, v130, v131
	v_mul_f32_e32 v130, 0xbfb8aa3b, v131
	v_exp_f32_e32 v130, v130
	s_nop 0
	v_add_f32_e32 v130, 1.0, v130
	v_rcp_f32_e32 v130, v130
	s_nop 0
	v_mul_f32_e32 v0, v0, v130
	v_cvt_pk_bf16_f32 v130, v132, v135
	v_cvt_pk_bf16_f32 v131, v141, v143
	v_cvt_pk_bf16_f32 v132, v133, v140
	v_add_co_u32_e32 v140, vcc, s26, v136
	v_cvt_pk_bf16_f32 v133, v142, v0
	s_mov_b32 s26, 0xa0000
	s_nop 0
	v_addc_co_u32_e32 v141, vcc, 0, v137, vcc
	global_store_dwordx4 v[140:141], v[130:133], off
	v_mov_b32_e32 v0, v238
	s_nop 0
	v_mov_b32_e32 v130, v30
	v_mov_b32_e32 v131, v22
	v_pk_mul_f32 v[130:131], v[130:131], v[0:1] op_sel_hi:[1,0]
	s_nop 0
	v_mul_f32_e32 v130, v130, v131
	v_mul_f32_e32 v131, 0xbfb8aa3b, v131
	v_exp_f32_e32 v131, v131
	s_nop 0
	v_add_f32_e32 v131, 1.0, v131
	v_rcp_f32_e32 v131, v131
	s_nop 0
	v_mul_f32_e32 v132, v130, v131
	v_mov_b32_e32 v130, v26
	v_mov_b32_e32 v131, v18
	v_pk_mul_f32 v[130:131], v[130:131], v[0:1] op_sel_hi:[1,0]
	s_nop 0
	v_mul_f32_e32 v130, v130, v131
	v_mul_f32_e32 v131, 0xbfb8aa3b, v131
	v_exp_f32_e32 v131, v131
	s_nop 0
	v_add_f32_e32 v131, 1.0, v131
	v_rcp_f32_e32 v131, v131
	s_nop 0
	v_mul_f32_e32 v133, v130, v131
	v_mov_b32_e32 v130, v31
	v_mov_b32_e32 v131, v23
	v_pk_mul_f32 v[130:131], v[130:131], v[0:1] op_sel_hi:[1,0]
	s_nop 0
	v_mul_f32_e32 v130, v130, v131
	v_mul_f32_e32 v131, 0xbfb8aa3b, v131
	v_exp_f32_e32 v131, v131
	s_nop 0
	v_add_f32_e32 v131, 1.0, v131
	v_rcp_f32_e32 v131, v131
	s_nop 0
	v_mul_f32_e32 v135, v130, v131
	v_mov_b32_e32 v130, v27
	v_mov_b32_e32 v131, v19
	v_pk_mul_f32 v[130:131], v[130:131], v[0:1] op_sel_hi:[1,0]
	s_nop 0
	v_mul_f32_e32 v130, v130, v131
	v_mul_f32_e32 v131, 0xbfb8aa3b, v131
	v_exp_f32_e32 v131, v131
	s_nop 0
	v_add_f32_e32 v131, 1.0, v131
	v_rcp_f32_e32 v131, v131
	s_nop 0
	v_mul_f32_e32 v140, v130, v131
	v_mov_b32_e32 v130, v32
	v_mov_b32_e32 v131, v24
	v_pk_mul_f32 v[130:131], v[130:131], v[0:1] op_sel_hi:[1,0]
	s_nop 0
	v_mul_f32_e32 v130, v130, v131
	v_mul_f32_e32 v131, 0xbfb8aa3b, v131
	v_exp_f32_e32 v131, v131
	s_nop 0
	v_add_f32_e32 v131, 1.0, v131
	v_rcp_f32_e32 v131, v131
	s_nop 0
	v_mul_f32_e32 v141, v130, v131
	v_mov_b32_e32 v130, v28
	v_mov_b32_e32 v131, v20
	v_pk_mul_f32 v[130:131], v[130:131], v[0:1] op_sel_hi:[1,0]
	s_nop 0
	v_mul_f32_e32 v130, v130, v131
	v_mul_f32_e32 v131, 0xbfb8aa3b, v131
	v_exp_f32_e32 v131, v131
	s_nop 0
	v_add_f32_e32 v131, 1.0, v131
	v_rcp_f32_e32 v131, v131
	s_nop 0
	v_mul_f32_e32 v142, v130, v131
	v_mov_b32_e32 v130, v33
	v_mov_b32_e32 v131, v25
	v_pk_mul_f32 v[130:131], v[130:131], v[0:1] op_sel_hi:[1,0]
	s_nop 0
	v_mul_f32_e32 v130, v130, v131
	v_mul_f32_e32 v131, 0xbfb8aa3b, v131
	v_exp_f32_e32 v131, v131
	s_nop 0
	v_add_f32_e32 v131, 1.0, v131
	v_rcp_f32_e32 v131, v131
	s_nop 0
	v_mul_f32_e32 v143, v130, v131
	v_mov_b32_e32 v130, v29
	v_mov_b32_e32 v131, v21
	v_pk_mul_f32 v[130:131], v[130:131], v[0:1] op_sel_hi:[1,0]
	s_nop 0
	v_mul_f32_e32 v0, v130, v131
	v_mul_f32_e32 v130, 0xbfb8aa3b, v131
	v_exp_f32_e32 v130, v130
	s_nop 0
	v_add_f32_e32 v130, 1.0, v130
	v_rcp_f32_e32 v130, v130
	s_nop 0
	v_mul_f32_e32 v0, v0, v130
	v_cvt_pk_bf16_f32 v130, v132, v135
	v_cvt_pk_bf16_f32 v131, v141, v143
	v_cvt_pk_bf16_f32 v132, v133, v140
	v_add_co_u32_e32 v140, vcc, s26, v136
	v_cvt_pk_bf16_f32 v133, v142, v0
	s_nop 1
	v_addc_co_u32_e32 v141, vcc, 0, v137, vcc
	global_store_dwordx4 v[140:141], v[130:133], off
	v_mov_b32_e32 v0, v239
	v_add_co_u32_e32 v136, vcc, 0xb0000, v136
	v_mov_b32_e32 v130, v14
	v_mov_b32_e32 v131, v6
	v_addc_co_u32_e32 v137, vcc, 0, v137, vcc
	v_pk_mul_f32 v[130:131], v[130:131], v[0:1] op_sel_hi:[1,0]
	s_nop 0
	v_mul_f32_e32 v130, v130, v131
	v_mul_f32_e32 v131, 0xbfb8aa3b, v131
	v_exp_f32_e32 v131, v131
	s_nop 0
	v_add_f32_e32 v131, 1.0, v131
	v_rcp_f32_e32 v131, v131
	s_nop 0
	v_mul_f32_e32 v132, v130, v131
	v_mov_b32_e32 v130, v10
	v_mov_b32_e32 v131, v2
	v_pk_mul_f32 v[130:131], v[130:131], v[0:1] op_sel_hi:[1,0]
	s_nop 0
	v_mul_f32_e32 v130, v130, v131
	v_mul_f32_e32 v131, 0xbfb8aa3b, v131
	v_exp_f32_e32 v131, v131
	s_nop 0
	v_add_f32_e32 v131, 1.0, v131
	v_rcp_f32_e32 v131, v131
	s_nop 0
	v_mul_f32_e32 v133, v130, v131
	v_mov_b32_e32 v130, v15
	v_mov_b32_e32 v131, v7
	v_pk_mul_f32 v[130:131], v[130:131], v[0:1] op_sel_hi:[1,0]
	s_nop 0
	v_mul_f32_e32 v130, v130, v131
	v_mul_f32_e32 v131, 0xbfb8aa3b, v131
	v_exp_f32_e32 v131, v131
	s_nop 0
	v_add_f32_e32 v131, 1.0, v131
	v_rcp_f32_e32 v131, v131
	s_nop 0
	v_mul_f32_e32 v135, v130, v131
	v_mov_b32_e32 v130, v11
	v_mov_b32_e32 v131, v3
	v_pk_mul_f32 v[130:131], v[130:131], v[0:1] op_sel_hi:[1,0]
	s_nop 0
	v_mul_f32_e32 v130, v130, v131
	v_mul_f32_e32 v131, 0xbfb8aa3b, v131
	v_exp_f32_e32 v131, v131
	s_nop 0
	v_add_f32_e32 v131, 1.0, v131
	v_rcp_f32_e32 v131, v131
	s_nop 0
	v_mul_f32_e32 v138, v130, v131
	v_mov_b32_e32 v130, v16
	v_mov_b32_e32 v131, v8
	v_pk_mul_f32 v[130:131], v[130:131], v[0:1] op_sel_hi:[1,0]
	s_nop 0
	v_mul_f32_e32 v130, v130, v131
	v_mul_f32_e32 v131, 0xbfb8aa3b, v131
	v_exp_f32_e32 v131, v131
	s_nop 0
	v_add_f32_e32 v131, 1.0, v131
	v_rcp_f32_e32 v131, v131
	s_nop 0
	v_mul_f32_e32 v139, v130, v131
	v_mov_b32_e32 v130, v12
	v_mov_b32_e32 v131, v4
	v_pk_mul_f32 v[130:131], v[130:131], v[0:1] op_sel_hi:[1,0]
	s_nop 0
	v_mul_f32_e32 v130, v130, v131
	v_mul_f32_e32 v131, 0xbfb8aa3b, v131
	v_exp_f32_e32 v131, v131
	s_nop 0
	v_add_f32_e32 v131, 1.0, v131
	v_rcp_f32_e32 v131, v131
	s_nop 0
	v_mul_f32_e32 v140, v130, v131
	v_mov_b32_e32 v130, v17
	v_mov_b32_e32 v131, v9
	v_pk_mul_f32 v[130:131], v[130:131], v[0:1] op_sel_hi:[1,0]
	s_nop 0
	v_mul_f32_e32 v130, v130, v131
	v_mul_f32_e32 v131, 0xbfb8aa3b, v131
	v_exp_f32_e32 v131, v131
	s_nop 0
	v_add_f32_e32 v131, 1.0, v131
	v_rcp_f32_e32 v131, v131
	s_nop 0
	v_mul_f32_e32 v141, v130, v131
	v_mov_b32_e32 v130, v13
	v_mov_b32_e32 v131, v5
	v_pk_mul_f32 v[130:131], v[130:131], v[0:1] op_sel_hi:[1,0]
	s_nop 0
	v_mul_f32_e32 v0, v130, v131
	v_mul_f32_e32 v130, 0xbfb8aa3b, v131
	v_exp_f32_e32 v130, v130
	s_nop 0
	v_add_f32_e32 v130, 1.0, v130
	v_rcp_f32_e32 v130, v130
	s_nop 0
	v_mul_f32_e32 v0, v0, v130
	v_cvt_pk_bf16_f32 v130, v132, v135
	v_cvt_pk_bf16_f32 v131, v139, v141
	v_cvt_pk_bf16_f32 v132, v133, v138
	v_cvt_pk_bf16_f32 v133, v140, v0
	global_store_dwordx4 v[136:137], v[130:133], off

.LBB0_378:
	s_andn2_b64 vcc, exec, s[44:45]
	s_cbranch_vccnz .LBB0_475
	v_ashrrev_i32_e32 v135, 31, v134
	v_lshl_add_u64 v[130:131], v[134:135], 2, s[86:87]
	v_mov_b32_e32 v132, v232
	s_cmp_lt_i32 s19, s62
	s_cselect_b64 vcc, -1, 0
	s_cmp_ge_i32 s19, s17
	v_mov_b32_e32 v0, 0x3e38aa3b
	s_cselect_b64 s[26:27], -1, 0
	s_cmp_lt_i32 s19, s63
	v_cndmask_b32_e32 v0, 1.0, v0, vcc
	s_cselect_b64 s[44:45], -1, 0
	s_and_b64 s[96:97], s[26:27], s[44:45]
	s_mov_b64 s[26:27], -1
	s_and_b64 vcc, exec, s[96:97]
	v_mul_f32_e32 v132, v0, v132
	v_pk_mul_f32 v[126:127], v[126:127], v[132:133] op_sel_hi:[1,0]
	v_pk_mul_f32 v[128:129], v[128:129], v[132:133] op_sel_hi:[1,0]
	v_pk_mul_f32 v[136:137], v[122:123], v[132:133] op_sel_hi:[1,0]
	v_pk_mul_f32 v[124:125], v[124:125], v[132:133] op_sel_hi:[1,0]
	s_cbranch_vccnz .LBB0_381
	s_mov_b64 s[26:27], 0

.LBB0_391:
	v_mov_b32_e32 v114, v233
	s_and_b64 vcc, exec, s[44:45]
	s_mov_b64 s[26:27], -1
	v_mul_f32_e32 v114, v0, v114
	s_waitcnt lgkmcnt(0)
	v_pk_mul_f32 v[112:113], v[112:113], v[114:115] op_sel_hi:[1,0]
	v_pk_mul_f32 v[116:117], v[110:111], v[114:115] op_sel_hi:[1,0]
	v_pk_mul_f32 v[110:111], v[108:109], v[114:115] op_sel_hi:[1,0]
	v_pk_mul_f32 v[118:119], v[106:107], v[114:115] op_sel_hi:[1,0]
	s_cbranch_vccnz .LBB0_393
	s_mov_b64 s[26:27], 0

.LBB0_403:
	v_mov_b32_e32 v98, v234
	s_and_b64 vcc, exec, s[44:45]
	s_mov_b64 s[26:27], -1
	v_mul_f32_e32 v98, v0, v98
	s_waitcnt lgkmcnt(0)
	v_pk_mul_f32 v[96:97], v[96:97], v[98:99] op_sel_hi:[1,0]
	v_pk_mul_f32 v[100:101], v[94:95], v[98:99] op_sel_hi:[1,0]
	v_pk_mul_f32 v[94:95], v[92:93], v[98:99] op_sel_hi:[1,0]
	v_pk_mul_f32 v[102:103], v[90:91], v[98:99] op_sel_hi:[1,0]
	s_cbranch_vccnz .LBB0_405
	s_mov_b64 s[26:27], 0

.LBB0_415:
	v_mov_b32_e32 v82, v235
	s_and_b64 vcc, exec, s[44:45]
	s_mov_b64 s[26:27], -1
	v_mul_f32_e32 v82, v0, v82
	s_waitcnt lgkmcnt(0)
	v_pk_mul_f32 v[80:81], v[80:81], v[82:83] op_sel_hi:[1,0]
	v_pk_mul_f32 v[84:85], v[78:79], v[82:83] op_sel_hi:[1,0]
	v_pk_mul_f32 v[78:79], v[76:77], v[82:83] op_sel_hi:[1,0]
	v_pk_mul_f32 v[86:87], v[74:75], v[82:83] op_sel_hi:[1,0]
	s_cbranch_vccnz .LBB0_417
	s_mov_b64 s[26:27], 0

.LBB0_427:
	v_mov_b32_e32 v66, v236
	s_and_b64 vcc, exec, s[44:45]
	s_mov_b64 s[26:27], -1
	v_mul_f32_e32 v66, v0, v66
	s_waitcnt lgkmcnt(0)
	v_pk_mul_f32 v[64:65], v[64:65], v[66:67] op_sel_hi:[1,0]
	v_pk_mul_f32 v[68:69], v[62:63], v[66:67] op_sel_hi:[1,0]
	v_pk_mul_f32 v[62:63], v[60:61], v[66:67] op_sel_hi:[1,0]
	v_pk_mul_f32 v[70:71], v[58:59], v[66:67] op_sel_hi:[1,0]
	s_cbranch_vccnz .LBB0_429
	s_mov_b64 s[26:27], 0

.LBB0_439:
	v_mov_b32_e32 v50, v237
	s_and_b64 vcc, exec, s[44:45]
	s_mov_b64 s[26:27], -1
	v_mul_f32_e32 v50, v0, v50
	s_waitcnt lgkmcnt(0)
	v_pk_mul_f32 v[48:49], v[48:49], v[50:51] op_sel_hi:[1,0]
	v_pk_mul_f32 v[52:53], v[46:47], v[50:51] op_sel_hi:[1,0]
	v_pk_mul_f32 v[46:47], v[44:45], v[50:51] op_sel_hi:[1,0]
	v_pk_mul_f32 v[54:55], v[42:43], v[50:51] op_sel_hi:[1,0]
	s_cbranch_vccnz .LBB0_441
	s_mov_b64 s[26:27], 0

.LBB0_451:
	v_mov_b32_e32 v34, v238
	s_and_b64 vcc, exec, s[44:45]
	s_mov_b64 s[26:27], -1
	v_mul_f32_e32 v34, v0, v34
	s_waitcnt lgkmcnt(0)
	v_pk_mul_f32 v[32:33], v[32:33], v[34:35] op_sel_hi:[1,0]
	v_pk_mul_f32 v[36:37], v[30:31], v[34:35] op_sel_hi:[1,0]
	v_pk_mul_f32 v[30:31], v[28:29], v[34:35] op_sel_hi:[1,0]
	v_pk_mul_f32 v[38:39], v[26:27], v[34:35] op_sel_hi:[1,0]
	s_cbranch_vccnz .LBB0_453
	s_mov_b64 s[26:27], 0

.LBB0_463:
	v_mov_b32_e32 v18, v239
	s_and_b64 vcc, exec, s[44:45]
	s_mov_b64 s[26:27], -1
	v_mul_f32_e32 v18, v0, v18
	s_waitcnt lgkmcnt(0)
	v_pk_mul_f32 v[16:17], v[16:17], v[18:19] op_sel_hi:[1,0]
	v_pk_mul_f32 v[20:21], v[14:15], v[18:19] op_sel_hi:[1,0]
	v_pk_mul_f32 v[14:15], v[12:13], v[18:19] op_sel_hi:[1,0]
	v_pk_mul_f32 v[22:23], v[10:11], v[18:19] op_sel_hi:[1,0]
	s_cbranch_vccnz .LBB0_465
	s_mov_b64 s[26:27], 0
